# mixprep sample-group LayerNorm items: one per workgroup (wave 0) instead of 8 per workgroup on the first 32
# speedup vs baseline: 1.0039x; 1.0039x over previous
.LBB0_340:
	s_or_b64 exec, exec, s[8:9]
	s_add_u32 s38, s34, 0x17200000
	v_and_b32_e32 v73, 63, v126
	s_addc_u32 s39, s35, 0
	s_mov_b32 s8, 8
	s_mov_b32 s42, 8
	s_mov_b32 s6, 9
	s_mov_b32 s40, 9
	s_mov_b32 s10, 10
	s_mov_b32 s4, 11
	s_lshr_b32 s98, s24, 3
	s_and_b32 s99, s24, 7
	s_cselect_b32 s98, 0x1000, s98
	s_cmpk_lt_i32 s26, 0x100
	s_cselect_b32 s98, s24, s98
	s_cmpk_gt_i32 s98, 0xff
	v_lshlrev_b32_e32 v72, 3, v73
	s_cbranch_scc1 .LBB0_343
	s_ashr_i32 s43, s42, 31
	v_mbcnt_hi_u32_b32 v0, -1, v165
	s_lshl_b64 s[42:43], s[42:43], 3
	v_and_b32_e32 v1, 64, v0
	s_add_u32 s42, s0, s42
	v_add_u32_e32 v1, 64, v1
	v_xor_b32_e32 v2, 1, v0
	s_addc_u32 s43, s1, s43
	s_ashr_i32 s41, s40, 31
	v_cmp_lt_i32_e32 vcc, v2, v1
	s_lshl_b64 s[40:41], s[40:41], 3
	s_add_u32 s44, s0, s40
	v_cndmask_b32_e32 v2, v0, v2, vcc
	v_lshlrev_b32_e32 v128, 2, v2
	v_xor_b32_e32 v2, 2, v0
	s_addc_u32 s45, s1, s41
	s_ashr_i32 s11, s10, 31
	v_cmp_lt_i32_e32 vcc, v2, v1
	s_lshl_b64 s[10:11], s[10:11], 3
	s_add_u32 s46, s0, s10
	v_cndmask_b32_e32 v2, v0, v2, vcc
	v_lshlrev_b32_e32 v129, 2, v2
	v_xor_b32_e32 v2, 4, v0
	s_addc_u32 s47, s1, s11
	s_ashr_i32 s5, s4, 31
	v_cmp_lt_i32_e32 vcc, v2, v1
	s_lshl_b64 s[4:5], s[4:5], 3
	s_add_u32 s4, s0, s4
	v_cndmask_b32_e32 v2, v0, v2, vcc
	v_lshlrev_b32_e32 v130, 2, v2
	v_xor_b32_e32 v2, 8, v0
	s_addc_u32 s5, s1, s5
	s_load_dwordx2 s[10:11], s[42:43], 0x0
	s_load_dwordx2 s[40:41], s[44:45], 0x0
	s_nop 0
	s_load_dwordx2 s[42:43], s[46:47], 0x0
	s_load_dwordx2 s[44:45], s[4:5], 0x0
	v_cmp_lt_i32_e32 vcc, v2, v1
	s_add_u32 s7, s20, 0x5908000
	s_addc_u32 s9, s21, 0
	v_cndmask_b32_e32 v2, v0, v2, vcc
	v_lshlrev_b32_e32 v131, 2, v2
	v_xor_b32_e32 v2, 16, v0
	v_cmp_lt_i32_e32 vcc, v2, v1
	s_lshl_b32 s3, s2, 12
	s_lshl_b32 s4, s77, 9
	v_cndmask_b32_e32 v2, v0, v2, vcc
	v_lshlrev_b32_e32 v132, 2, v2
	v_xor_b32_e32 v2, 32, v0
	v_cmp_lt_i32_e32 vcc, v2, v1
	s_add_i32 s19, s3, s4
	s_lshl_b32 s19, s98, 9
	s_lshl_b32 s3, s2, 5
	s_lshl_b32 s4, s77, 2
	v_cndmask_b32_e32 v0, v0, v2, vcc
	v_mov_b32_e32 v75, 0
	v_lshlrev_b32_e32 v74, 4, v73
	s_add_i32 s29, s3, s4
	s_lshl_b32 s29, s98, 2
	s_mov_b32 s4, 0x358637bd
	v_lshlrev_b32_e32 v133, 2, v0
	v_lshl_add_u64 v[76:77], s[14:15], 0, v[74:75]
	s_lshl_b32 s25, s26, 12
	s_lshl_b32 s47, s26, 5
	v_lshlrev_b32_e32 v78, 1, v72
	v_mov_b32_e32 v79, v75
	s_movk_i32 s64, 0x5000
	s_mov_b32 s65, 0x9000
	s_mov_b32 s66, 0xe000
	s_mov_b32 s46, 0x3a800000
	v_mov_b64_e32 v[80:81], s[4:5]
	s_mov_b32 s67, 0x800000
	v_mov_b32_e32 v134, 0x4800
	s_mov_b32 s68, s98
